# pool phase: 10 row loads issued before one wait (was load-wait-ds_write per row); window-sum LDS loop prefetches next ds_read
# speedup vs baseline: 1.0024x; 1.0024x over previous
; #define LAS __attribute__((address_space(3)))
; __device__ __forceinline__ void pool_units(CArgsP a, int l, LAS unsigned char* lds) {
;     ...
;         for (int idx = tid; idx < 80 * 64; idx += 512) { const int i = idx >> 6, ch = idx & 63, t = t0 - 8 + i;
;             u32x4 v = {0u, 0u, 0u, 0u}; if (t >= 0 && t < L) v = *(const u32x4*)(POOL + (size_t)(rowbase + t) * 512 + ch * 8);
;             *(LAS u32x4*)(RAW + i * 520 + ch * 8) = v; }
.LBB0_357:
	s_lshl_b32 s29, s28, 6
	s_cmpk_lt_i32 s28, 0x200
	s_movk_i32 s30, 0x7c0
	s_cselect_b32 s30, s30, 0xc0
	s_cselect_b32 s48, 0x800, s37
	s_and_b32 s49, s30, s29
	s_and_saveexec_b64 s[30:31], s[40:41]
	s_cbranch_execz .LBB0_362
	s_sub_i32 s46, s29, s49
	s_add_i32 s47, s49, -8
	v_ashrrev_i32_e32 v85, 6, v123
	v_add_u32_e32 v86, s47, v85
	v_mad_u64_u32 v[210:211], s[44:45], v85, s59, v[122:123]
	v_add_u32_e32 v212, s46, v86
	v_ashrrev_i32_e32 v213, 31, v212
	v_lshlrev_b64 v[212:213], 10, v[212:213]
	v_lshl_add_u64 v[212:213], v[120:121], 0, v[212:213]
	s_mov_b64 s[98:99], exec
	v_cmp_gt_u32_e32 vcc, s48, v86
	v_mov_b32_e32 v188, 0
	v_mov_b32_e32 v189, 0
	v_mov_b32_e32 v190, 0
	v_mov_b32_e32 v191, 0
	s_and_b64 exec, s[98:99], vcc
	global_load_dwordx4 v[188:191], v[212:213], off
	s_mov_b64 exec, s[98:99]
	v_add_co_u32_e32 v212, vcc, 0x2000, v212
	s_nop 1
	v_addc_co_u32_e32 v213, vcc, 0, v213, vcc
	v_add_u32_e32 v86, 8, v86
	v_cmp_gt_u32_e32 vcc, s48, v86
	v_mov_b32_e32 v192, 0
	v_mov_b32_e32 v193, 0
	v_mov_b32_e32 v194, 0
	v_mov_b32_e32 v195, 0
	s_and_b64 exec, s[98:99], vcc
	global_load_dwordx4 v[192:195], v[212:213], off
	s_mov_b64 exec, s[98:99]
	v_add_co_u32_e32 v212, vcc, 0x2000, v212
	s_nop 1
	v_addc_co_u32_e32 v213, vcc, 0, v213, vcc
	v_add_u32_e32 v86, 8, v86
	v_cmp_gt_u32_e32 vcc, s48, v86
	v_mov_b32_e32 v196, 0
	v_mov_b32_e32 v197, 0
	v_mov_b32_e32 v198, 0
	v_mov_b32_e32 v199, 0
	s_and_b64 exec, s[98:99], vcc
	global_load_dwordx4 v[196:199], v[212:213], off
	s_mov_b64 exec, s[98:99]
	v_add_co_u32_e32 v212, vcc, 0x2000, v212
	s_nop 1
	v_addc_co_u32_e32 v213, vcc, 0, v213, vcc
	v_add_u32_e32 v86, 8, v86
	v_cmp_gt_u32_e32 vcc, s48, v86
	v_mov_b32_e32 v200, 0
	v_mov_b32_e32 v201, 0
	v_mov_b32_e32 v202, 0
	v_mov_b32_e32 v203, 0
	s_and_b64 exec, s[98:99], vcc
	global_load_dwordx4 v[200:203], v[212:213], off
	s_mov_b64 exec, s[98:99]
	v_add_co_u32_e32 v212, vcc, 0x2000, v212
	s_nop 1
	v_addc_co_u32_e32 v213, vcc, 0, v213, vcc
	v_add_u32_e32 v86, 8, v86
	v_cmp_gt_u32_e32 vcc, s48, v86
	v_mov_b32_e32 v204, 0
	v_mov_b32_e32 v205, 0
	v_mov_b32_e32 v206, 0
	v_mov_b32_e32 v207, 0
	s_and_b64 exec, s[98:99], vcc
	global_load_dwordx4 v[204:207], v[212:213], off
	s_mov_b64 exec, s[98:99]
	v_add_co_u32_e32 v212, vcc, 0x2000, v212
	s_nop 1
	v_addc_co_u32_e32 v213, vcc, 0, v213, vcc
	v_add_u32_e32 v86, 8, v86
	v_cmp_gt_u32_e32 vcc, s48, v86
	v_mov_b32_e32 v218, 0
	v_mov_b32_e32 v219, 0
	v_mov_b32_e32 v220, 0
	v_mov_b32_e32 v221, 0
	s_and_b64 exec, s[98:99], vcc
	global_load_dwordx4 v[218:221], v[212:213], off
	s_mov_b64 exec, s[98:99]
	v_add_co_u32_e32 v212, vcc, 0x2000, v212
	s_nop 1
	v_addc_co_u32_e32 v213, vcc, 0, v213, vcc
	v_add_u32_e32 v86, 8, v86
	v_cmp_gt_u32_e32 vcc, s48, v86
	v_mov_b32_e32 v222, 0
	v_mov_b32_e32 v223, 0
	v_mov_b32_e32 v224, 0
	v_mov_b32_e32 v225, 0
	s_and_b64 exec, s[98:99], vcc
	global_load_dwordx4 v[222:225], v[212:213], off
	s_mov_b64 exec, s[98:99]
	v_add_co_u32_e32 v212, vcc, 0x2000, v212
	s_nop 1
	v_addc_co_u32_e32 v213, vcc, 0, v213, vcc
	v_add_u32_e32 v86, 8, v86
	v_cmp_gt_u32_e32 vcc, s48, v86
	v_mov_b32_e32 v226, 0
	v_mov_b32_e32 v227, 0
	v_mov_b32_e32 v228, 0
	v_mov_b32_e32 v229, 0
	s_and_b64 exec, s[98:99], vcc
	global_load_dwordx4 v[226:229], v[212:213], off
	s_mov_b64 exec, s[98:99]
	v_add_co_u32_e32 v212, vcc, 0x2000, v212
	s_nop 1
	v_addc_co_u32_e32 v213, vcc, 0, v213, vcc
	v_add_u32_e32 v86, 8, v86
	v_cmp_gt_u32_e32 vcc, s48, v86
	v_mov_b32_e32 v230, 0
	v_mov_b32_e32 v231, 0
	v_mov_b32_e32 v232, 0
	v_mov_b32_e32 v233, 0
	s_and_b64 exec, s[98:99], vcc
	global_load_dwordx4 v[230:233], v[212:213], off
	s_mov_b64 exec, s[98:99]
	v_add_co_u32_e32 v212, vcc, 0x2000, v212
	s_nop 1
	v_addc_co_u32_e32 v213, vcc, 0, v213, vcc
	v_add_u32_e32 v86, 8, v86
	v_cmp_gt_u32_e32 vcc, s48, v86
	v_mov_b32_e32 v234, 0
	v_mov_b32_e32 v235, 0
	v_mov_b32_e32 v236, 0
	v_mov_b32_e32 v237, 0
	s_and_b64 exec, s[98:99], vcc
	global_load_dwordx4 v[234:237], v[212:213], off
	s_mov_b64 exec, s[98:99]
	s_waitcnt vmcnt(0)
	ds_write_b128 v210, v[188:191]
	ds_write_b128 v210, v[192:195] offset:8320
	ds_write_b128 v210, v[196:199] offset:16640
	ds_write_b128 v210, v[200:203] offset:24960
	ds_write_b128 v210, v[204:207] offset:33280
	ds_write_b128 v210, v[218:221] offset:41600
	ds_write_b128 v210, v[222:225] offset:49920
	ds_write_b128 v210, v[226:229] offset:58240
	v_add_u32_e32 v210, 0x10400, v210
	ds_write_b128 v210, v[230:233]
	ds_write_b128 v210, v[234:237] offset:8320

; __device__ __forceinline__ float bflo(unsigned w) { return __uint_as_float(w << 16); }
; __device__ __forceinline__ float bfhi(unsigned w) { return __uint_as_float(w & 0xffff0000u); }
; #define LAS __attribute__((address_space(3)))
; __device__ __forceinline__ void pool_units(CArgsP a, int l, LAS unsigned char* lds) {
;     ...
;             for (int tau = lo; tau < hb; ++tau) { const u32x4 v = *(const LAS u32x4*)(RAW + (tau - t0 + 8) * 520 + ch * 8);
; #pragma unroll
;                 for (int j = 0; j < 4; ++j) { sm[2 * j] += bflo(v[j]); sm[2 * j + 1] += bfhi(v[j]); } }
.LBB0_365:
	v_ashrrev_i32_e32 v92, 6, v81
	v_add_u32_e32 v82, s49, v92
	v_sub_u32_e32 v83, v82, v127
	v_add_u32_e32 v82, v82, v127
	v_max_i32_e32 v93, 0, v83
	v_min_i32_e32 v94, s48, v82
	v_mov_b32_e32 v83, 0
	v_cmp_gt_i32_e32 vcc, v94, v93
	v_mov_b32_e32 v82, v83
	v_mov_b32_e32 v85, v83
	v_mov_b32_e32 v84, v83
	v_mov_b32_e32 v87, v83
	v_mov_b32_e32 v86, v83
	v_mov_b32_e32 v89, v83
	v_mov_b32_e32 v88, v83
	s_and_saveexec_b64 s[44:45], vcc
	s_cbranch_execz .LBB0_364
	v_mad_u64_u32 v[90:91], s[46:47], v93, s59, v[80:81]
	v_mov_b32_e32 v82, 0
	s_mov_b64 s[46:47], 0
	v_mov_b32_e32 v91, v93
	v_mov_b32_e32 v83, v82
	v_mov_b32_e32 v88, v82
	v_mov_b32_e32 v89, v82
	v_mov_b32_e32 v86, v82
	v_mov_b32_e32 v87, v82
	v_mov_b32_e32 v84, v82
	v_mov_b32_e32 v85, v82
	ds_read_b128 v[96:99], v90
	v_add_u32_e32 v90, 0x410, v90
.LBB0_367:
	v_add_u32_e32 v91, 1, v91
	v_cmp_ge_i32_e32 vcc, v91, v94
	s_or_b64 s[46:47], vcc, s[46:47]
	s_waitcnt lgkmcnt(0)
	v_mov_b32_e32 v188, v96
	v_mov_b32_e32 v189, v97
	v_mov_b32_e32 v190, v98
	v_mov_b32_e32 v191, v99
	ds_read_b128 v[96:99], v90
	v_add_u32_e32 v90, 0x410, v90
	v_lshlrev_b32_e32 v100, 16, v188
	v_and_b32_e32 v101, 0xffff0000, v188
	v_lshlrev_b32_e32 v192, 16, v189
	v_and_b32_e32 v193, 0xffff0000, v189
	v_pk_add_f32 v[86:87], v[86:87], v[192:193]
	v_lshlrev_b32_e32 v192, 16, v190
	v_and_b32_e32 v193, 0xffff0000, v190
	v_pk_add_f32 v[84:85], v[84:85], v[192:193]
	v_lshlrev_b32_e32 v192, 16, v191
	v_and_b32_e32 v193, 0xffff0000, v191
	v_pk_add_f32 v[88:89], v[88:89], v[100:101]
	v_pk_add_f32 v[82:83], v[82:83], v[192:193]
	s_andn2_b64 exec, exec, s[46:47]
	s_cbranch_execnz .LBB0_367
	s_or_b64 exec, exec, s[46:47]
	s_waitcnt lgkmcnt(0)
	s_branch .LBB0_364
